# H + indexer phase roles by wave parity (even waves score, odd waves select) - SIMD placement of the two roles
# baseline (speedup 1.0000x reference)
; __device__ __forceinline__ void phase3(const Params& p, LAS unsigned char* lds, int bid, int nblk, int tid, int wave, int lane) {
;     for (int j = bid; j < 256; j += nblk) {
;         const int b = j >> 5, cp = j & 31;
;         for (int it = 0; it <= 16; ++it) {
;             const int role = (wave >> 1) & 1, ridx = (wave & 1) + 2 * (wave >> 2);
;             if (it == 0) idx_scores8(p, lds, b, 63 - cp, 0, ridx + 4 * role, lane, 8);
;             else if (role == 0) { if (it < 16) { const int c = it < 8 ? 63 - cp : cp; idx_scores8(p, lds + (it & 1) * 65536, b, c, it & 7, ridx, lane, 4); } }
;             else { const int i1 = it - 1; const int c = i1 < 8 ? 63 - cp : cp; idx_select8(p, lds + (i1 & 1) * 65536, b, c, i1 & 7, ridx, lane); }
.LBB0_597:
	s_or_b64 exec, exec, s[0:1]
	s_cmpk_lt_i32 s85, 0x100
	s_cselect_b64 s[0:1], -1, 0
	s_waitcnt vmcnt(3) lgkmcnt(0)
	v_mov_b32_e32 v0, v167
	s_movk_i32 s48, 0x100
	v_writelane_b32 v243, s0, 56
	s_cmpk_gt_i32 s85, 0xff
	s_movk_i32 s29, 0xff
	s_barrier
	v_writelane_b32 v243, s1, 57
	s_cbranch_scc1 .LBB0_3699
	s_lshr_b32 s0, s86, 7
	s_bfe_u32 s2, s86, 0x10006
	s_and_b32 s3, s0, 0x1fffffe
	s_or_b32 s6, s3, s2
	s_bfe_u32 s6, s86, 0x20007
	s_bitcmp1_b32 s86, 6
	v_writelane_b32 v243, s84, 58
	s_cselect_b64 s[34:35], -1, 0
	s_lshl_b32 s0, s6, 1
	v_and_b32_e32 v76, 63, v0
	v_writelane_b32 v243, s0, 59
	s_lshl_b32 s0, s6, 14
	v_writelane_b32 v243, s87, 60
	s_add_i32 s49, s0, 0
	v_cmp_eq_u32_e64 s[0:1], 3, v76
	s_mov_b32 s93, 0
	s_mov_b32 s7, s93
	v_writelane_b32 v243, s0, 32
	s_mov_b32 s45, s93
	v_and_b32_e32 v2, 3, v0
	v_writelane_b32 v243, s1, 33
	v_cmp_eq_u32_e64 s[0:1], 4, v76
	v_bfe_u32 v3, v0, 1, 5
	s_waitcnt vmcnt(2)
	v_bfe_u32 v4, v0, 4, 1
	v_writelane_b32 v243, s0, 61
	v_lshlrev_b32_e32 v1, 10, v0
	v_and_or_b32 v80, v3, 2, v4
	v_writelane_b32 v243, s1, 62
	v_cmp_eq_u32_e64 s[0:1], 5, v76
	v_and_or_b32 v2, v3, 4, v2
	v_and_b32_e32 v3, 31, v0
	v_writelane_b32 v243, s0, 63
	v_and_b32_e32 v83, 0xc00, v1
	v_bfe_u32 v1, v0, 5, 1
	v_writelane_b32 v242, s1, 0
	v_cmp_eq_u32_e64 s[0:1], 6, v76
	v_and_b32_e32 v4, 32, v0
	v_lshlrev_b32_e32 v0, 4, v3
	v_writelane_b32 v242, s0, 1
	v_mov_b32_e32 v79, 0
	v_lshl_or_b32 v78, v1, 11, v0
	v_writelane_b32 v242, s1, 2
	v_cmp_eq_u32_e64 s[0:1], 7, v76
	v_lshlrev_b32_e32 v82, 1, v1
	v_lshlrev_b32_e32 v5, 14, v1
	v_writelane_b32 v242, s0, 3
	v_lshl_add_u64 v[0:1], s[80:81], 0, v[78:79]
	v_mov_b64_e32 v[86:87], s[82:83]
	v_writelane_b32 v242, s1, 4
	v_cmp_eq_u32_e64 s[0:1], 8, v76
	v_cmp_eq_u32_e64 s[42:43], 0, v76
	v_cmp_eq_u32_e64 s[38:39], 1, v76
	v_writelane_b32 v242, s0, 5
	v_cmp_eq_u32_e64 s[36:37], 2, v76
	v_lshlrev_b32_e32 v77, 2, v76
	v_writelane_b32 v242, s1, 6
	v_cmp_eq_u32_e64 s[0:1], 9, v76
	v_xor_b32_e32 v106, 0xfc, v77
	v_lshlrev_b32_e32 v2, 6, v2
	v_writelane_b32 v242, s0, 7
	v_lshlrev_b32_e32 v88, 1, v4
	v_lshlrev_b32_e32 v81, 4, v76
	v_writelane_b32 v242, s1, 8
	v_cmp_eq_u32_e64 s[0:1], 10, v76
	v_lshlrev_b32_e32 v107, 2, v106
	v_xor_b32_e32 v108, 0xfd, v77
	v_writelane_b32 v242, s0, 9
	v_xor_b32_e32 v109, 0xfe, v77
	v_xor_b32_e32 v110, 0xff, v77
	v_writelane_b32 v242, s1, 10
	v_cmp_eq_u32_e64 s[0:1], 11, v76
	v_or_b32_e32 v111, 0x100, v76
	v_mov_b32_e32 v114, 0x2a00
	v_writelane_b32 v242, s0, 11
	v_lshlrev_b32_e32 v78, 1, v2
	v_mov_b32_e32 v90, v88
	v_writelane_b32 v242, s1, 12
	v_cmp_eq_u32_e64 s[0:1], 12, v76
	v_mov_b32_e32 v91, v79
	s_mov_b32 s47, 0xffff
	v_writelane_b32 v242, s0, 13
	s_mov_b32 s33, 0x80008000
	v_mov_b32_e32 v115, 1
	v_writelane_b32 v242, s1, 14
	v_cmp_eq_u32_e64 s[0:1], 13, v76
	s_nop 1
	v_writelane_b32 v242, s0, 15
	s_nop 1
	v_writelane_b32 v242, s1, 16
	v_cmp_eq_u32_e64 s[0:1], 14, v76
	s_nop 1
	v_writelane_b32 v242, s0, 17
	s_nop 1
	v_writelane_b32 v242, s1, 18
	v_cmp_eq_u32_e64 s[0:1], 15, v76
	s_nop 1
	v_writelane_b32 v242, s0, 19
	s_nop 1
	v_writelane_b32 v242, s1, 20
	v_cmp_eq_u32_e64 s[0:1], 16, v76
	s_nop 1
	v_writelane_b32 v242, s0, 21
	s_nop 1
	v_writelane_b32 v242, s1, 22
	v_cmp_eq_u32_e64 s[0:1], 17, v76
	s_nop 1
	v_writelane_b32 v242, s0, 23
	s_nop 1
	v_writelane_b32 v242, s1, 24
	v_cmp_eq_u32_e64 s[0:1], 18, v76
	s_nop 1
	v_writelane_b32 v242, s0, 25
	s_nop 1
	v_writelane_b32 v242, s1, 26
	v_cmp_eq_u32_e64 s[0:1], 19, v76
	s_nop 1
	v_writelane_b32 v242, s0, 27
	s_nop 1
	v_writelane_b32 v242, s1, 28
	v_cmp_eq_u32_e64 s[0:1], 20, v76
	s_nop 1
	v_writelane_b32 v242, s0, 29
	s_nop 1
	v_writelane_b32 v242, s1, 30
	v_cmp_eq_u32_e64 s[0:1], 21, v76
	s_nop 1
	v_writelane_b32 v242, s0, 31
	s_nop 1
	v_writelane_b32 v242, s1, 32
	v_cmp_eq_u32_e64 s[0:1], 22, v76
	s_nop 1
	v_writelane_b32 v242, s0, 33
	s_nop 1
	v_writelane_b32 v242, s1, 34
	v_cmp_eq_u32_e64 s[0:1], 23, v76
	s_nop 1
	v_writelane_b32 v242, s0, 35
	s_nop 1
	v_writelane_b32 v242, s1, 36
	v_cmp_eq_u32_e64 s[0:1], 24, v76
	s_nop 1
	v_writelane_b32 v242, s0, 37
	s_nop 1
	v_writelane_b32 v242, s1, 38
	v_cmp_eq_u32_e64 s[0:1], 25, v76
	s_nop 1
	v_writelane_b32 v242, s0, 39
	s_nop 1
	v_writelane_b32 v242, s1, 40
	v_cmp_eq_u32_e64 s[0:1], 26, v76
	s_nop 1
	v_writelane_b32 v242, s0, 41
	s_nop 1
	v_writelane_b32 v242, s1, 42
	v_cmp_eq_u32_e64 s[0:1], 27, v76
	s_nop 1
	v_writelane_b32 v242, s0, 43
	s_nop 1
	v_writelane_b32 v242, s1, 44
	v_cmp_eq_u32_e64 s[0:1], 28, v76
	s_nop 1
	v_writelane_b32 v242, s0, 45
	s_nop 1
	v_writelane_b32 v242, s1, 46
	v_cmp_eq_u32_e64 s[0:1], 29, v76
	s_nop 1
	v_writelane_b32 v242, s0, 47
	s_nop 1
	v_writelane_b32 v242, s1, 48
	s_lshl_b64 s[0:1], s[6:7], 12
	v_writelane_b32 v242, s0, 49
	s_nop 1
	v_writelane_b32 v242, s1, 50
	s_lshr_b32 s0, s86, 4
	s_and_b32 s4, s0, 4
	s_mov_b32 s0, s6
	v_writelane_b32 v242, s0, 51
	s_add_i32 s44, s6, s4
	s_nop 0
	v_writelane_b32 v242, s1, 52
	s_lshl_b64 s[0:1], s[44:45], 12
	v_writelane_b32 v242, s0, 53
	s_nop 1
	v_writelane_b32 v242, s1, 54
	s_add_u32 s0, s80, 0x1400000
	s_addc_u32 s1, s81, 0
	v_writelane_b32 v242, s0, 55
	s_add_i32 s4, s4, s3
	s_nop 0
	v_writelane_b32 v242, s1, 56
	s_mov_b64 s[0:1], 0x1000000
	v_lshl_add_u64 v[84:85], v[0:1], 0, s[0:1]
	s_lshr_b32 s0, s86, 2
	s_and_b32 s0, s0, 0x3fffffc0
	s_lshl_b32 s1, s2, 5
	s_or_b32 s0, s0, s1
	s_lshl_b32 s0, s6, 5
	v_writelane_b32 v242, s86, 57
	v_or_b32_e32 v0, s0, v3
	v_writelane_b32 v242, s0, 58
	v_lshlrev_b32_e32 v0, 2, v0
	s_mov_b32 s0, s44
	v_add3_u32 v112, v5, v0, 0
	s_lshl_b32 s97, s0, 5
	v_lshl_add_u32 v0, s0, 7, v5
	v_writelane_b32 v242, s85, 59
	v_cmp_eq_u32_e64 s[0:1], 30, v76
	v_lshl_or_b32 v0, v3, 2, v0
	v_add_u32_e32 v113, 0, v0
	v_writelane_b32 v242, s0, 60
	s_nop 1
	v_writelane_b32 v242, s1, 61
	v_cmp_eq_u32_e64 s[0:1], 31, v76
	s_nop 1
	v_writelane_b32 v242, s0, 62
	s_nop 1
	v_writelane_b32 v242, s1, 63
	v_cmp_eq_u32_e64 s[0:1], 63, v76
	s_nop 1
	v_writelane_b32 v241, s0, 0
	s_nop 1
	v_writelane_b32 v241, s1, 1
	v_writelane_b32 v241, s76, 2
	s_mov_b32 s0, s44
	s_nop 0
	v_writelane_b32 v241, s77, 3
	v_writelane_b32 v241, s78, 4
	v_writelane_b32 v241, s79, 5
	v_writelane_b32 v241, s80, 6
	v_writelane_b32 v241, s81, 7
	v_writelane_b32 v241, s82, 8
	v_writelane_b32 v241, s83, 9
	v_writelane_b32 v241, s34, 10
	s_nop 1
	v_writelane_b32 v241, s35, 11
	v_writelane_b32 v241, s49, 12
	v_writelane_b32 v241, s42, 13
	s_nop 1
	v_writelane_b32 v241, s43, 14
	v_writelane_b32 v241, s38, 15
	s_nop 1
	v_writelane_b32 v241, s39, 16
	v_writelane_b32 v241, s36, 17
	s_nop 1
	v_writelane_b32 v241, s37, 18
	v_writelane_b32 v241, s0, 19
	s_nop 1
	v_writelane_b32 v241, s1, 20
	v_writelane_b32 v241, s97, 21
	s_branch .LBB0_600
